# prompt attention: V^T LDS image permuted per 16-key group so each V fragment is one conflict-free ds_read_b128
# baseline (speedup 1.0000x reference)
.LBB0_73:
	v_readlane_b32 s0, v247, 23
	v_readlane_b32 s1, v247, 24
	s_and_b64 vcc, exec, s[0:1]
	s_cbranch_vccz .LBB0_101
	s_waitcnt vmcnt(0)
	v_ashrrev_i32_e32 v2, 3, v222
	v_ashrrev_i32_e32 v3, 31, v2
	v_and_b32_e32 v5, 64, v191
	v_lshlrev_b64 v[146:147], 13, v[2:3]
	v_xor_b32_e32 v3, 32, v191
	v_add_u32_e32 v5, 64, v5
	s_movk_i32 s0, 0xc0
	v_lshlrev_b32_e32 v4, 3, v222
	v_cmp_lt_i32_e32 vcc, v3, v5
	v_cmp_gt_i32_e64 s[4:5], s0, v222
	v_ashrrev_i32_e32 v168, 4, v222
	v_and_b32_e32 v0, 0x78, v4
	s_mov_b64 s[0:1], 0x80000
	v_cndmask_b32_e32 v3, v191, v3, vcc
	v_and_b32_e32 v4, 56, v4
	v_lshl_add_u64 v[150:151], v[146:147], 0, s[0:1]
	v_lshlrev_b32_e32 v170, 2, v3
	s_movk_i32 s0, 0x90
	v_mul_lo_u32 v3, v168, s97
	v_lshlrev_b32_e32 v5, 1, v0
	s_add_u32 s2, s16, 0x20900000
	v_add3_u32 v173, 0, v3, v5
	v_mul_lo_u32 v2, v2, s0
	v_and_b32_e32 v3, 48, v4
	v_and_b32_e32 v5, 8, v4
	v_lshl_or_b32 v3, v3, 1, v5
	v_lshl_add_u32 v176, v155, 4, 0
	s_addc_u32 s3, s17, 0
	s_lshl_b32 s6, s62, 5
	v_add3_u32 v174, 0, v2, v3
	v_sub_u32_e32 v177, v176, v154
	s_ashr_i32 s18, s56, 7
	v_lshlrev_b32_e32 v167, 4, v222
	v_and_or_b32 v169, s6, 32, v149
	v_mul_u32_u24_e32 v171, 0x90, v149
	v_mad_u32_u24 v172, v149, s0, v220
	v_add_u32_e32 v175, 0x2400, v174
	v_mad_u32_u24 v180, v149, s0, v176
	v_add_u32_e32 v181, 0xc0, v168
	v_lshlrev_b32_e32 v0, 1, v0
	v_lshlrev_b32_e32 v152, 1, v4
	v_lshlrev_b32_e32 v154, 1, v154
	v_lshlrev_b32_e32 v156, 1, v148
	v_readlane_b32 s19, v247, 22
	s_branch .LBB0_76

.LBB0_78:
	s_or_b64 exec, exec, s[0:1]
	s_lshl_b32 s0, s19, 2
	s_ashr_i32 s7, s19, 8
	s_and_b32 s21, s0, 60
	s_add_i32 s22, s21, s18
	s_lshl_b32 s0, s7, 12
	s_lshl_b32 s10, s22, 6
	s_ashr_i32 s1, s0, 31
	s_add_i32 s11, s10, s0
	s_or_b32 s23, s21, 3
	s_lshl_b64 s[0:1], s[0:1], 12
	s_add_u32 s0, s2, s0
	s_addc_u32 s1, s3, s1
	s_lshl_b32 s20, s6, 7
	s_lshl_b32 s88, s6, 8
	s_add_u32 s0, s0, s88
	v_sub_u32_e64 v14, s21, 8 clamp
	s_addc_u32 s1, s1, 0
	s_lshl_b32 s7, s7, 4
	s_or_b32 s6, s7, s6
	v_lshl_add_u32 v2, v14, 6, v168
	s_ashr_i32 s7, s6, 31
	v_ashrrev_i32_e32 v3, 31, v2
	s_lshl_b64 s[6:7], s[6:7], 20
	v_readlane_b32 s12, v245, 54
	v_lshlrev_b64 v[4:5], 12, v[2:3]
	s_add_u32 s6, s12, s6
	v_readlane_b32 s12, v245, 55
	v_lshl_add_u64 v[4:5], s[0:1], 0, v[4:5]
	s_addc_u32 s7, s12, s7
	v_lshl_add_u64 v[4:5], v[4:5], 0, v[0:1]
	s_mov_b32 s12, 0x20000
	v_add_u32_e32 v2, 64, v2
	v_add_co_u32_e32 v6, vcc, s12, v4
	v_ashrrev_i32_e32 v3, 31, v2
	s_nop 0
	v_addc_co_u32_e32 v7, vcc, 0, v5, vcc
	v_lshlrev_b64 v[2:3], 12, v[2:3]
	global_load_dwordx4 v[82:85], v[4:5], off
	global_load_dwordx4 v[86:89], v[6:7], off
	v_lshl_add_u64 v[4:5], s[6:7], 0, v[146:147]
	v_lshlrev_b32_e32 v6, 7, v14
	v_mov_b32_e32 v7, v1
	v_lshl_add_u64 v[10:11], s[6:7], 0, v[150:151]
	v_lshl_add_u64 v[2:3], s[0:1], 0, v[2:3]
	v_lshl_add_u64 v[8:9], v[4:5], 0, v[6:7]
	v_mov_b32_e32 v153, v1
	v_lshl_add_u64 v[6:7], v[10:11], 0, v[6:7]
	v_lshl_add_u64 v[2:3], v[2:3], 0, v[0:1]
	v_lshl_add_u64 v[8:9], v[8:9], 0, v[152:153]
	v_lshl_add_u64 v[6:7], v[6:7], 0, v[152:153]
	v_add_co_u32_e32 v12, vcc, s12, v2
	global_load_dwordx4 v[90:93], v[8:9], off
	global_load_dwordx4 v[94:97], v[6:7], off
	v_addc_co_u32_e32 v13, vcc, 0, v3, vcc
	global_load_dwordx4 v[98:101], v[2:3], off
	global_load_dwordx4 v[110:113], v[12:13], off
	global_load_dwordx4 v[138:141], v[8:9], off offset:128
	v_or_b32_e32 v2, s11, v169
	v_ashrrev_i32_e32 v3, 31, v2
	v_lshlrev_b64 v[8:9], 12, v[2:3]
	v_lshl_add_u64 v[8:9], s[46:47], 0, v[8:9]
	v_lshl_add_u64 v[8:9], v[8:9], 0, s[88:89]
	v_mov_b32_e32 v155, v1
	v_lshl_add_u64 v[8:9], v[8:9], 0, v[154:155]
	global_load_dwordx4 v[102:105], v[8:9], off
	global_load_dwordx4 v[106:109], v[8:9], off offset:32
	global_load_dwordx4 v[114:117], v[8:9], off offset:64
	global_load_dwordx4 v[118:121], v[8:9], off offset:96
	global_load_dwordx4 v[122:125], v[8:9], off offset:128
	global_load_dwordx4 v[126:129], v[8:9], off offset:160
	global_load_dwordx4 v[130:133], v[8:9], off offset:192
	global_load_dwordx4 v[134:137], v[8:9], off offset:224
	global_load_dwordx4 v[142:145], v[6:7], off offset:128
	v_mov_b32_e32 v6, s66
	v_mov_b32_e32 v50, v1
	v_mov_b32_e32 v51, v1
	v_mov_b32_e32 v52, v1
	v_mov_b32_e32 v53, v1
	v_mov_b32_e32 v54, v1
	v_mov_b32_e32 v55, v1
	v_mov_b32_e32 v56, v1
	v_mov_b32_e32 v57, v1
	v_mov_b32_e32 v58, v1
	v_readfirstlane_b32 s31, v14
	v_lshlrev_b64 v[158:159], 11, v[2:3]
	v_lshl_add_u64 v[162:163], v[4:5], 0, v[152:153]
	v_lshl_add_u64 v[164:165], v[10:11], 0, v[152:153]
	v_mov_b32_e32 v59, v1
	v_mov_b32_e32 v60, v1
	v_mov_b32_e32 v61, v1
	v_mov_b32_e32 v62, v1
	v_mov_b32_e32 v63, v1
	v_mov_b32_e32 v64, v1
	v_mov_b32_e32 v65, v1
	v_mov_b64_e32 v[34:35], v[50:51]
	v_mov_b64_e32 v[18:19], v[50:51]
	s_mov_b32 s50, 0x20000
	v_or_b32_e32 v155, s10, v169
	v_lshl_add_u64 v[160:161], s[0:1], 0, v[0:1]
	s_add_i32 s26, s22, -8
	v_mov_b32_e32 v182, 0xf149f2ca
	v_mov_b32_e32 v153, 0
	v_mov_b64_e32 v[36:37], v[52:53]
	v_mov_b64_e32 v[38:39], v[54:55]
	v_mov_b64_e32 v[40:41], v[56:57]
	s_waitcnt vmcnt(15)
	ds_write_b128 v173, v[82:85]
	s_waitcnt vmcnt(14)
	ds_write_b128 v173, v[86:89] offset:8704
	v_add_u32_e32 v66, 0x4400, v174
	v_add_u32_e32 v67, 0x4400, v175
	s_waitcnt vmcnt(13)
	ds_write2_b64 v66, v[90:91], v[92:93] offset1:2
	s_waitcnt vmcnt(12)
	ds_write2_b64 v67, v[94:95], v[96:97] offset1:2
	s_waitcnt lgkmcnt(0)
	s_barrier
	s_waitcnt vmcnt(1)
	ds_read_b32 v157, v6
	v_mov_b64_e32 v[2:3], v[50:51]
	v_mov_b64_e32 v[42:43], v[58:59]
	v_mov_b64_e32 v[44:45], v[60:61]
	v_mov_b64_e32 v[46:47], v[62:63]
	v_mov_b64_e32 v[48:49], v[64:65]
	v_mov_b64_e32 v[20:21], v[52:53]
	v_mov_b64_e32 v[22:23], v[54:55]
	v_mov_b64_e32 v[24:25], v[56:57]
	v_mov_b64_e32 v[26:27], v[58:59]
	v_mov_b64_e32 v[28:29], v[60:61]
	v_mov_b64_e32 v[30:31], v[62:63]
	v_mov_b64_e32 v[32:33], v[64:65]
	v_mov_b64_e32 v[4:5], v[52:53]
	v_mov_b64_e32 v[6:7], v[54:55]
	v_mov_b64_e32 v[8:9], v[56:57]
	v_mov_b64_e32 v[10:11], v[58:59]
	v_mov_b64_e32 v[12:13], v[60:61]
	v_mov_b64_e32 v[14:15], v[62:63]
	v_mov_b64_e32 v[16:17], v[64:65]

.Lpa0_tile:
	v_or_b32_e32 v66, s33, v149
	v_mad_u32_u24 v188, v66, s97, v176
	ds_read_b128 v[206:209], v188
	ds_read_b128 v[210:213], v188 offset:32
	ds_read_b128 v[214:217], v188 offset:64
	ds_read_b128 v[224:227], v188 offset:96
	ds_read_b128 v[232:235], v188 offset:128
	ds_read_b128 v[236:239], v188 offset:160
	ds_read_b128 v[240:243], v188 offset:192
	ds_read_b128 v[184:187], v188 offset:224
	v_add_u32_e32 v190, s33, v183
	v_lshl_add_u32 v197, s33, 1, v180
	v_cmp_gt_i32_e64 s[12:13], s61, v190
	v_cmp_lt_i32_e64 s[0:1], s64, v190
	s_waitcnt lgkmcnt(7)
	v_mfma_f32_32x32x16_bf16 v[66:81], v[206:209], v[102:105], 0
	s_waitcnt lgkmcnt(6)
	v_mfma_f32_32x32x16_bf16 v[66:81], v[210:213], v[106:109], v[66:81]
	s_waitcnt lgkmcnt(5)
	v_mfma_f32_32x32x16_bf16 v[66:81], v[214:217], v[114:117], v[66:81]
	s_waitcnt lgkmcnt(4)
	v_mfma_f32_32x32x16_bf16 v[66:81], v[224:227], v[118:121], v[66:81]
	s_waitcnt lgkmcnt(3)
	v_mfma_f32_32x32x16_bf16 v[66:81], v[232:235], v[122:125], v[66:81]
	s_waitcnt lgkmcnt(2)
	v_mfma_f32_32x32x16_bf16 v[66:81], v[236:239], v[126:129], v[66:81]
	s_waitcnt lgkmcnt(1)
	v_mfma_f32_32x32x16_bf16 v[66:81], v[240:243], v[130:133], v[66:81]
	s_waitcnt lgkmcnt(0)
	v_mfma_f32_32x32x16_bf16 v[66:81], v[184:187], v[134:137], v[66:81]
	s_and_saveexec_b64 s[14:15], s[0:1]
	s_cbranch_execz .Lpa0_nobias
	v_add_u32_e32 v190, v190, v148
	v_med3_i32 v188, v190, s39, 63
	v_lshl_add_u32 v188, v188, 2, s66
	v_add_u32_e32 v192, 1, v190
	v_med3_i32 v192, v192, s39, 63
	v_lshl_add_u32 v192, v192, 2, s66
	v_add_u32_e32 v193, 2, v190
	v_med3_i32 v193, v193, s39, 63
	v_lshl_add_u32 v193, v193, 2, s66
	v_add_u32_e32 v194, 3, v190
	v_med3_i32 v194, v194, s39, 63
	v_lshl_add_u32 v194, v194, 2, s66
	v_add_u32_e32 v195, 8, v190
	v_med3_i32 v195, v195, s39, 63
	v_lshl_add_u32 v195, v195, 2, s66
	v_add_u32_e32 v196, 9, v190
	v_med3_i32 v196, v196, s39, 63
	v_lshl_add_u32 v196, v196, 2, s66
	v_add_u32_e32 v199, 10, v190
	v_med3_i32 v199, v199, s39, 63
	v_lshl_add_u32 v199, v199, 2, s66
	v_add_u32_e32 v200, 11, v190
	v_med3_i32 v200, v200, s39, 63
	v_lshl_add_u32 v200, v200, 2, s66
	v_add_u32_e32 v202, 16, v190
	v_med3_i32 v202, v202, s39, 63
	v_lshl_add_u32 v202, v202, 2, s66
	v_add_u32_e32 v204, 17, v190
	v_med3_i32 v204, v204, s39, 63
	v_lshl_add_u32 v204, v204, 2, s66
	v_add_u32_e32 v205, 18, v190
	v_med3_i32 v205, v205, s39, 63
	v_lshl_add_u32 v205, v205, 2, s66
	v_add_u32_e32 v218, 19, v190
	v_med3_i32 v218, v218, s39, 63
	v_lshl_add_u32 v218, v218, 2, s66
	v_add_u32_e32 v219, 24, v190
	v_med3_i32 v219, v219, s39, 63
	v_lshl_add_u32 v219, v219, 2, s66
	v_add_u32_e32 v223, 25, v190
	v_med3_i32 v223, v223, s39, 63
	v_lshl_add_u32 v223, v223, 2, s66
	v_add_u32_e32 v244, 26, v190
	v_med3_i32 v244, v244, s39, 63
	v_lshl_add_u32 v244, v244, 2, s66
	v_add_u32_e32 v190, 27, v190
	v_med3_i32 v190, v190, s39, 63
	v_lshl_add_u32 v190, v190, 2, s66
	ds_read_b32 v188, v188 offset:512
	ds_read_b32 v192, v192 offset:512
	ds_read_b32 v193, v193 offset:512
	ds_read_b32 v194, v194 offset:512
	ds_read_b32 v195, v195 offset:512
	ds_read_b32 v196, v196 offset:512
	ds_read_b32 v199, v199 offset:512
	ds_read_b32 v200, v200 offset:512
	ds_read_b32 v202, v202 offset:512
	ds_read_b32 v204, v204 offset:512
	ds_read_b32 v205, v205 offset:512
	ds_read_b32 v218, v218 offset:512
	ds_read_b32 v219, v219 offset:512
	ds_read_b32 v223, v223 offset:512
	ds_read_b32 v244, v244 offset:512
	ds_read_b32 v190, v190 offset:512
	s_mov_b64 exec, s[14:15]
	ds_read_b128 v[206:209], v197 offset:17408
	ds_read_b128 v[210:213], v197 offset:22016
	ds_read_b128 v[214:217], v197 offset:26624
	ds_read_b128 v[224:227], v197 offset:31232
	ds_read_b128 v[232:235], v197 offset:17440
	ds_read_b128 v[236:239], v197 offset:22048
	ds_read_b128 v[240:243], v197 offset:26656
	ds_read_b128 v[184:187], v197 offset:31264
	s_waitcnt lgkmcnt(8)
	s_and_b64 exec, s[14:15], s[0:1]
	v_add_f32_e32 v66, v66, v188
	v_add_f32_e32 v67, v67, v192
	v_add_f32_e32 v68, v68, v193
	v_add_f32_e32 v69, v69, v194
	v_add_f32_e32 v70, v70, v195
	v_add_f32_e32 v71, v71, v196
	v_add_f32_e32 v72, v72, v199
	v_add_f32_e32 v73, v73, v200
	v_add_f32_e32 v74, v74, v202
	v_add_f32_e32 v75, v75, v204
	v_add_f32_e32 v76, v76, v205
	v_add_f32_e32 v77, v77, v218
	v_add_f32_e32 v78, v78, v219
	v_add_f32_e32 v79, v79, v223
	v_add_f32_e32 v80, v80, v244
	v_add_f32_e32 v81, v81, v190
	s_mov_b64 exec, s[14:15]
	s_branch .Lpa0_max
.Lpa0_nobias:
	s_mov_b64 exec, s[14:15]
	ds_read_b128 v[206:209], v197 offset:17408
	ds_read_b128 v[210:213], v197 offset:22016
	ds_read_b128 v[214:217], v197 offset:26624
	ds_read_b128 v[224:227], v197 offset:31232
	ds_read_b128 v[232:235], v197 offset:17440
	ds_read_b128 v[236:239], v197 offset:22048
	ds_read_b128 v[240:243], v197 offset:26656
	ds_read_b128 v[184:187], v197 offset:31264
	s_nop 1

.Lpa_w88_done:
	s_cmp_gt_u32 s31, s21
	ds_write_b128 v173, v[98:101] offset:35840
	ds_write_b128 v173, v[110:113] offset:44544
	v_add_u32_e32 v66, 0xd000, v174
	v_add_u32_e32 v67, 0xd000, v175
	ds_write2_b64 v66, v[138:139], v[140:141] offset1:2
	ds_write2_b64 v67, v[142:143], v[144:145] offset1:2
	s_waitcnt lgkmcnt(0)
	s_barrier
	s_cbranch_scc1 .LBB0_90
	v_lshl_add_u32 v66, s31, 6, v181
	v_ashrrev_i32_e32 v67, 31, v66
	v_lshlrev_b64 v[66:67], 12, v[66:67]
	v_lshl_add_u64 v[66:67], v[160:161], 0, v[66:67]
	v_add_co_u32_e32 v68, vcc, 0x20000, v66
	s_lshl_b32 s88, s31, 7
	s_nop 0
	v_addc_co_u32_e32 v69, vcc, 0, v67, vcc
	global_load_dwordx4 v[98:101], v[66:67], off
	global_load_dwordx4 v[110:113], v[68:69], off
	v_lshl_add_u64 v[66:67], v[162:163], 0, s[88:89]
	v_lshl_add_u64 v[68:69], v[164:165], 0, s[88:89]
	global_load_dwordx4 v[138:141], v[66:67], off offset:384
	global_load_dwordx4 v[142:145], v[68:69], off offset:384

.Lpa1_tile:
	v_or_b32_e32 v66, s33, v149
	v_mad_u32_u24 v188, v66, s97, v176
	ds_read_b128 v[206:209], v188 offset:35840
	ds_read_b128 v[210:213], v188 offset:35872
	ds_read_b128 v[214:217], v188 offset:35904
	ds_read_b128 v[224:227], v188 offset:35936
	ds_read_b128 v[232:235], v188 offset:35968
	ds_read_b128 v[236:239], v188 offset:36000
	ds_read_b128 v[240:243], v188 offset:36032
	ds_read_b128 v[184:187], v188 offset:36064
	v_add_u32_e32 v190, s33, v183
	v_lshl_add_u32 v197, s33, 1, v180
	v_cmp_gt_i32_e64 s[12:13], s61, v190
	v_cmp_lt_i32_e64 s[0:1], s64, v190
	v_add_u32_e32 v197, 0x8c00, v197
	s_waitcnt lgkmcnt(7)
	v_mfma_f32_32x32x16_bf16 v[66:81], v[206:209], v[102:105], 0
	s_waitcnt lgkmcnt(6)
	v_mfma_f32_32x32x16_bf16 v[66:81], v[210:213], v[106:109], v[66:81]
	s_waitcnt lgkmcnt(5)
	v_mfma_f32_32x32x16_bf16 v[66:81], v[214:217], v[114:117], v[66:81]
	s_waitcnt lgkmcnt(4)
	v_mfma_f32_32x32x16_bf16 v[66:81], v[224:227], v[118:121], v[66:81]
	s_waitcnt lgkmcnt(3)
	v_mfma_f32_32x32x16_bf16 v[66:81], v[232:235], v[122:125], v[66:81]
	s_waitcnt lgkmcnt(2)
	v_mfma_f32_32x32x16_bf16 v[66:81], v[236:239], v[126:129], v[66:81]
	s_waitcnt lgkmcnt(1)
	v_mfma_f32_32x32x16_bf16 v[66:81], v[240:243], v[130:133], v[66:81]
	s_waitcnt lgkmcnt(0)
	v_mfma_f32_32x32x16_bf16 v[66:81], v[184:187], v[134:137], v[66:81]
	s_and_saveexec_b64 s[14:15], s[0:1]
	s_cbranch_execz .Lpa1_nobias
	v_add_u32_e32 v190, v190, v148
	v_med3_i32 v188, v190, s39, 63
	v_lshl_add_u32 v188, v188, 2, s66
	v_add_u32_e32 v192, 1, v190
	v_med3_i32 v192, v192, s39, 63
	v_lshl_add_u32 v192, v192, 2, s66
	v_add_u32_e32 v193, 2, v190
	v_med3_i32 v193, v193, s39, 63
	v_lshl_add_u32 v193, v193, 2, s66
	v_add_u32_e32 v194, 3, v190
	v_med3_i32 v194, v194, s39, 63
	v_lshl_add_u32 v194, v194, 2, s66
	v_add_u32_e32 v195, 8, v190
	v_med3_i32 v195, v195, s39, 63
	v_lshl_add_u32 v195, v195, 2, s66
	v_add_u32_e32 v196, 9, v190
	v_med3_i32 v196, v196, s39, 63
	v_lshl_add_u32 v196, v196, 2, s66
	v_add_u32_e32 v199, 10, v190
	v_med3_i32 v199, v199, s39, 63
	v_lshl_add_u32 v199, v199, 2, s66
	v_add_u32_e32 v200, 11, v190
	v_med3_i32 v200, v200, s39, 63
	v_lshl_add_u32 v200, v200, 2, s66
	v_add_u32_e32 v202, 16, v190
	v_med3_i32 v202, v202, s39, 63
	v_lshl_add_u32 v202, v202, 2, s66
	v_add_u32_e32 v204, 17, v190
	v_med3_i32 v204, v204, s39, 63
	v_lshl_add_u32 v204, v204, 2, s66
	v_add_u32_e32 v205, 18, v190
	v_med3_i32 v205, v205, s39, 63
	v_lshl_add_u32 v205, v205, 2, s66
	v_add_u32_e32 v218, 19, v190
	v_med3_i32 v218, v218, s39, 63
	v_lshl_add_u32 v218, v218, 2, s66
	v_add_u32_e32 v219, 24, v190
	v_med3_i32 v219, v219, s39, 63
	v_lshl_add_u32 v219, v219, 2, s66
	v_add_u32_e32 v223, 25, v190
	v_med3_i32 v223, v223, s39, 63
	v_lshl_add_u32 v223, v223, 2, s66
	v_add_u32_e32 v244, 26, v190
	v_med3_i32 v244, v244, s39, 63
	v_lshl_add_u32 v244, v244, 2, s66
	v_add_u32_e32 v190, 27, v190
	v_med3_i32 v190, v190, s39, 63
	v_lshl_add_u32 v190, v190, 2, s66
	ds_read_b32 v188, v188 offset:512
	ds_read_b32 v192, v192 offset:512
	ds_read_b32 v193, v193 offset:512
	ds_read_b32 v194, v194 offset:512
	ds_read_b32 v195, v195 offset:512
	ds_read_b32 v196, v196 offset:512
	ds_read_b32 v199, v199 offset:512
	ds_read_b32 v200, v200 offset:512
	ds_read_b32 v202, v202 offset:512
	ds_read_b32 v204, v204 offset:512
	ds_read_b32 v205, v205 offset:512
	ds_read_b32 v218, v218 offset:512
	ds_read_b32 v219, v219 offset:512
	ds_read_b32 v223, v223 offset:512
	ds_read_b32 v244, v244 offset:512
	ds_read_b32 v190, v190 offset:512
	s_mov_b64 exec, s[14:15]
	ds_read_b128 v[206:209], v197 offset:17408
	ds_read_b128 v[210:213], v197 offset:22016
	ds_read_b128 v[214:217], v197 offset:26624
	ds_read_b128 v[224:227], v197 offset:31232
	ds_read_b128 v[232:235], v197 offset:17440
	ds_read_b128 v[236:239], v197 offset:22048
	ds_read_b128 v[240:243], v197 offset:26656
	ds_read_b128 v[184:187], v197 offset:31264
	s_waitcnt lgkmcnt(8)
	s_and_b64 exec, s[14:15], s[0:1]
	v_add_f32_e32 v66, v66, v188
	v_add_f32_e32 v67, v67, v192
	v_add_f32_e32 v68, v68, v193
	v_add_f32_e32 v69, v69, v194
	v_add_f32_e32 v70, v70, v195
	v_add_f32_e32 v71, v71, v196
	v_add_f32_e32 v72, v72, v199
	v_add_f32_e32 v73, v73, v200
	v_add_f32_e32 v74, v74, v202
	v_add_f32_e32 v75, v75, v204
	v_add_f32_e32 v76, v76, v205
	v_add_f32_e32 v77, v77, v218
	v_add_f32_e32 v78, v78, v219
	v_add_f32_e32 v79, v79, v223
	v_add_f32_e32 v80, v80, v244
	v_add_f32_e32 v81, v81, v190
	s_mov_b64 exec, s[14:15]
	s_branch .Lpa1_max

.LBB0_97:
	s_andn2_b64 vcc, exec, s[10:11]
	s_cbranch_vccnz .LBB0_99
	s_waitcnt vmcnt(4)
	ds_write_b128 v173, v[82:85]
	ds_write_b128 v173, v[86:89] offset:8704
	v_add_u32_e32 v66, 0x4400, v174
	v_add_u32_e32 v67, 0x4400, v175
	ds_write2_b64 v66, v[90:91], v[92:93] offset1:2
	ds_write2_b64 v67, v[94:95], v[96:97] offset1:2
